# adds: GLA scan output stores use the default cache policy (were nt) so the combine phase finds them cached
# speedup vs baseline: 1.0015x; 1.0015x over previous
.LBB0_1331:
	s_waitcnt lgkmcnt(0)
	s_barrier
	ds_read_b128 v[26:29], v60 offset:53248
	ds_read_b128 v[22:25], v60 offset:53312
	s_andn2_b64 vcc, exec, s[72:73]
	s_cbranch_vccnz .Lgl_su
	ds_read_b128 v[176:179], v104 offset:62464
	ds_read_b128 v[180:183], v104 offset:62528
	ds_read_b128 v[184:187], v62
	ds_read_b128 v[188:191], v92
	ds_read_b128 v[192:195], v62 offset:64
	ds_read_b128 v[196:199], v93
	ds_read_b128 v[200:203], v62 offset:128
	ds_read_b128 v[216:219], v94
	ds_read_b128 v[220:223], v62 offset:192
	ds_read_b128 v[224:227], v95
	s_waitcnt lgkmcnt(8)
	v_mfma_f32_16x16x32_bf16 v[248:251], v[26:29], v[176:179], 0
	ds_read_b128 v[176:179], v105 offset:62464
	v_mfma_f32_16x16x32_bf16 v[248:251], v[22:25], v[180:183], v[248:251]
	ds_read_b128 v[180:183], v105 offset:62528
	s_waitcnt lgkmcnt(6)
	v_mfma_f32_16x16x32_bf16 v[248:251], v[184:187], v[188:191], v[248:251]
	ds_read_b128 v[188:191], v97
	v_mfma_f32_16x16x32_bf16 v[248:251], v[192:195], v[196:199], v[248:251]
	ds_read_b128 v[196:199], v98
	s_waitcnt lgkmcnt(4)
	v_mfma_f32_16x16x32_bf16 v[248:251], v[200:203], v[216:219], v[248:251]
	ds_read_b128 v[216:219], v99
	v_mfma_f32_16x16x32_bf16 v[248:251], v[220:223], v[224:227], v[248:251]
	ds_read_b128 v[224:227], v100
	s_waitcnt lgkmcnt(4)
	v_mfma_f32_16x16x32_bf16 v[236:239], v[26:29], v[176:179], 0
	ds_read_b128 v[176:179], v101
	v_mfma_f32_16x16x32_bf16 v[236:239], v[22:25], v[180:183], v[236:239]
	ds_read_b128 v[180:183], v106 offset:34816
	s_waitcnt lgkmcnt(4)
	v_mfma_f32_16x16x32_bf16 v[236:239], v[184:187], v[188:191], v[236:239]
	ds_read_b128 v[184:187], v106 offset:34880
	ds_read_b128 v[188:191], v101 offset:64
	v_mfma_f32_16x16x32_bf16 v[236:239], v[192:195], v[196:199], v[236:239]
	ds_read_b128 v[192:195], v107 offset:34816
	ds_read_b128 v[196:199], v107 offset:34880
	s_waitcnt lgkmcnt(6)
	v_mfma_f32_16x16x32_bf16 v[236:239], v[200:203], v[216:219], v[236:239]
	ds_read_b128 v[200:203], v101 offset:128
	ds_read_b128 v[216:219], v108 offset:34816
	v_mfma_f32_16x16x32_bf16 v[236:239], v[220:223], v[224:227], v[236:239]
	ds_read_b128 v[220:223], v108 offset:34880
	ds_read_b128 v[224:227], v101 offset:192
	s_waitcnt lgkmcnt(8)
	v_pk_mul_f32 v[4:5], v[4:5], v[178:179]
	v_pk_mul_f32 v[2:3], v[2:3], v[176:177]
	ds_read_b128 v[176:179], v109 offset:34816
	s_nop 0
	v_mfma_f32_16x16x32_bf16 v[2:5], v[180:183], v[26:29], v[2:5]
	ds_read_b128 v[180:183], v109 offset:34880
	s_waitcnt lgkmcnt(8)
	v_mfma_f32_16x16x32_bf16 v[2:5], v[184:187], v[22:25], v[2:5]
	v_pk_mul_f32 v[16:17], v[16:17], v[190:191]
	v_pk_mul_f32 v[14:15], v[14:15], v[188:189]
	s_nop 1
	s_waitcnt lgkmcnt(6)
	v_mfma_f32_16x16x32_bf16 v[14:17], v[192:195], v[26:29], v[14:17]
	v_mfma_f32_16x16x32_bf16 v[14:17], v[196:199], v[22:25], v[14:17]
	s_waitcnt lgkmcnt(4)
	v_pk_mul_f32 v[8:9], v[8:9], v[202:203]
	v_pk_mul_f32 v[6:7], v[6:7], v[200:201]
	s_nop 1
	v_mfma_f32_16x16x32_bf16 v[6:9], v[216:219], v[26:29], v[6:9]
	s_waitcnt lgkmcnt(2)
	v_mfma_f32_16x16x32_bf16 v[6:9], v[220:223], v[22:25], v[6:9]
	v_pk_mul_f32 v[12:13], v[12:13], v[226:227]
	v_pk_mul_f32 v[10:11], v[10:11], v[224:225]
	s_nop 1
	s_waitcnt lgkmcnt(0)
	v_mfma_f32_16x16x32_bf16 v[10:13], v[176:179], v[26:29], v[10:13]
	v_mfma_f32_16x16x32_bf16 v[10:13], v[180:183], v[22:25], v[10:13]
	v_add_u32_e32 v204, s76, v41
	v_ashrrev_i32_e32 v205, 31, v204
	v_cvt_pk_bf16_f32 v248, v248, v249
	v_cvt_pk_bf16_f32 v249, v250, v251
	v_lshlrev_b64 v[250:251], 11, v[204:205]
	v_lshl_add_u64 v[250:251], v[50:51], 0, v[250:251]
	global_store_dwordx2 v[250:251], v[248:249], off
	v_add_u32_e32 v204, s76, v142
	v_ashrrev_i32_e32 v205, 31, v204
	v_cvt_pk_bf16_f32 v236, v236, v237
	v_cvt_pk_bf16_f32 v237, v238, v239
	v_lshlrev_b64 v[238:239], 11, v[204:205]
	v_lshl_add_u64 v[238:239], v[50:51], 0, v[238:239]
	global_store_dwordx2 v[238:239], v[236:237], off
	s_branch .LBB0_1316
